# DSA softmax section rewritten by hand: 2-op masks, max3 tree, running-max clamp, packed partial sums
# speedup vs baseline: 1.0111x; 1.0111x over previous
; __device__ __forceinline__ float max_x32(float v) { const unsigned u = __float_as_uint(v); auto r = __builtin_amdgcn_permlane32_swap(u, u, false, false); return fmaxf(__uint_as_float(r[0]), __uint_as_float(r[1])); }
; template <bool MASKED>
; __device__ __forceinline__ void softmax_tile(f32x16& s0, f32x16& s1, float& m, float& l, float& alpha, unsigned mlo, unsigned mhi, bf16x8 (&pk)[4]) {
;     ...
;     if (MASKED) {
; #pragma unroll
;         for (int r = 0; r < 16; ++r) { const int bit = (r & 3) + 8 * (r >> 2); if (!((mlo >> bit) & 1u)) s0[r] = NEG; if (!((mhi >> bit) & 1u)) s1[r] = NEG; }
;     }
;     float mx = fmaxf(s0[0], s1[0]);
; #pragma unroll
;     for (int r = 1; r < 16; ++r) mx = fmaxf(mx, fmaxf(s0[r], s1[r]));
;     mx = max_x32(mx);
;     const float mn = fmaxf(m, mx);
;     alpha = __builtin_amdgcn_exp2f(m - mn); m = mn;
.LBB0_1176:
	s_andn2_b64 vcc, exec, s[12:13]
	s_cbranch_vccnz .LBB0_1180
	s_mul_i32 s12, s17, 0xa000
	s_add_i32 s12, s12, 0
	v_add_u32_e32 v194, s12, v141
	v_add_u32_e32 v70, v194, v143
	v_add_u32_e32 v74, v194, v144
	ds_read_b128 v[66:69], v70
	ds_read_b128 v[70:73], v70 offset:8192
	ds_read_b128 v[160:163], v74
	ds_read_b128 v[164:167], v74 offset:8192
	v_add_u32_e32 v74, v194, v145
	ds_read_b128 v[168:171], v74
	ds_read_b128 v[172:175], v74 offset:8192
	v_add_u32_e32 v74, v194, v146
	ds_read_b128 v[186:189], v74 offset:8192
	ds_read_b128 v[190:193], v74
	s_waitcnt lgkmcnt(0)
	v_mfma_f32_32x32x16_bf16 v[82:97], v[66:69], v[98:101], 0
	v_mfma_f32_32x32x16_bf16 v[66:81], v[70:73], v[98:101], 0
	v_mfma_f32_32x32x16_bf16 v[82:97], v[160:163], v[102:105], v[82:97]
	v_mfma_f32_32x32x16_bf16 v[66:81], v[164:167], v[102:105], v[66:81]
	v_mfma_f32_32x32x16_bf16 v[82:97], v[168:171], v[106:109], v[82:97]
	v_mfma_f32_32x32x16_bf16 v[66:81], v[172:175], v[106:109], v[66:81]
	v_mfma_f32_32x32x16_bf16 v[82:97], v[190:193], v[110:113], v[82:97]
	v_mfma_f32_32x32x16_bf16 v[66:81], v[186:189], v[110:113], v[66:81]
	v_add_u32_e32 v164, v194, v147
	v_add_u32_e32 v172, v194, v148
	v_add_u32_e32 v190, v194, v149
	v_add_u32_e32 v198, v194, v150
	ds_read_b128 v[160:163], v164
	ds_read_b128 v[164:167], v164 offset:8192
	ds_read_b128 v[168:171], v172
	ds_read_b128 v[172:175], v172 offset:8192
	ds_read_b128 v[186:189], v190
	ds_read_b128 v[190:193], v190 offset:8192
	ds_read_b128 v[194:197], v198 offset:8192
	ds_read_b128 v[206:209], v198
	s_waitcnt lgkmcnt(0)
	v_mfma_f32_32x32x16_bf16 v[82:97], v[160:163], v[114:117], v[82:97]
	v_mfma_f32_32x32x16_bf16 v[66:81], v[164:167], v[114:117], v[66:81]
	v_mfma_f32_32x32x16_bf16 v[82:97], v[168:171], v[118:121], v[82:97]
	v_mfma_f32_32x32x16_bf16 v[66:81], v[172:175], v[118:121], v[66:81]
	v_mfma_f32_32x32x16_bf16 v[82:97], v[186:189], v[122:125], v[82:97]
	v_mfma_f32_32x32x16_bf16 v[66:81], v[190:193], v[122:125], v[66:81]
	v_mfma_f32_32x32x16_bf16 v[82:97], v[206:209], v[126:129], v[82:97]
	v_mfma_f32_32x32x16_bf16 v[66:81], v[194:197], v[126:129], v[66:81]
	v_bfe_i32 v160, v185, 0, 1
	v_bfe_i32 v161, v185, 1, 1
	v_bfe_i32 v162, v185, 2, 1
	v_bfe_i32 v163, v185, 3, 1
	v_bfe_i32 v164, v185, 8, 1
	v_bfe_i32 v165, v185, 9, 1
	v_bfe_i32 v166, v185, 10, 1
	v_bfe_i32 v167, v185, 11, 1
	v_bfe_i32 v168, v185, 16, 1
	v_bfe_i32 v169, v185, 17, 1
	v_bfe_i32 v170, v185, 18, 1
	v_bfe_i32 v171, v185, 19, 1
	v_bfe_i32 v172, v185, 24, 1
	v_bfe_i32 v173, v185, 25, 1
	v_bfe_i32 v174, v185, 26, 1
	v_bfe_i32 v175, v185, 27, 1
	v_bfe_i32 v186, v0, 0, 1
	v_bfe_i32 v187, v0, 1, 1
	v_bfe_i32 v188, v0, 2, 1
	v_bfe_i32 v189, v0, 3, 1
	v_bfe_i32 v190, v0, 8, 1
	v_bfe_i32 v191, v0, 9, 1
	v_bfe_i32 v192, v0, 10, 1
	v_bfe_i32 v193, v0, 11, 1
	v_bfe_i32 v194, v0, 16, 1
	v_bfe_i32 v195, v0, 17, 1
	v_bfe_i32 v196, v0, 18, 1
	v_bfe_i32 v197, v0, 19, 1
	v_bfe_i32 v198, v0, 24, 1
	v_bfe_i32 v199, v0, 25, 1
	v_bfe_i32 v206, v0, 26, 1
	v_bfe_i32 v207, v0, 27, 1
	v_bfi_b32 v82, v160, v82, v215
	v_bfi_b32 v83, v161, v83, v215
	v_bfi_b32 v84, v162, v84, v215
	v_bfi_b32 v85, v163, v85, v215
	v_bfi_b32 v86, v164, v86, v215
	v_bfi_b32 v87, v165, v87, v215
	v_bfi_b32 v88, v166, v88, v215
	v_bfi_b32 v89, v167, v89, v215
	v_bfi_b32 v90, v168, v90, v215
	v_bfi_b32 v91, v169, v91, v215
	v_bfi_b32 v92, v170, v92, v215
	v_bfi_b32 v93, v171, v93, v215
	v_bfi_b32 v94, v172, v94, v215
	v_bfi_b32 v95, v173, v95, v215
	v_bfi_b32 v96, v174, v96, v215
	v_bfi_b32 v97, v175, v97, v215
	v_bfi_b32 v66, v186, v66, v215
	v_bfi_b32 v67, v187, v67, v215
	v_bfi_b32 v68, v188, v68, v215
	v_bfi_b32 v69, v189, v69, v215
	v_bfi_b32 v70, v190, v70, v215
	v_bfi_b32 v71, v191, v71, v215
	v_bfi_b32 v72, v192, v72, v215
	v_bfi_b32 v73, v193, v73, v215
	v_bfi_b32 v74, v194, v74, v215
	v_bfi_b32 v75, v195, v75, v215
	v_bfi_b32 v76, v196, v76, v215
	v_bfi_b32 v77, v197, v77, v215
	v_bfi_b32 v78, v198, v78, v215
	v_bfi_b32 v79, v199, v79, v215
	v_bfi_b32 v80, v206, v80, v215
	v_bfi_b32 v81, v207, v81, v215
	v_max3_f32 v160, v82, v83, v84
	v_max3_f32 v161, v85, v86, v87
	v_max3_f32 v162, v88, v89, v90
	v_max3_f32 v163, v91, v92, v93
	v_max3_f32 v164, v94, v95, v96
	v_max3_f32 v165, v97, v66, v67
	v_max3_f32 v166, v68, v69, v70
	v_max3_f32 v167, v71, v72, v73
	v_max3_f32 v168, v74, v75, v76
	v_max3_f32 v169, v77, v78, v79
	v_max3_f32 v160, v160, v161, v162
	v_max3_f32 v163, v163, v164, v165
	v_max3_f32 v166, v166, v167, v168
	v_max3_f32 v169, v169, v80, v81
	v_max3_f32 v160, v160, v163, v166
	v_max_f32_e32 v160, v160, v169
	v_mov_b32_e32 v161, v160
	s_nop 1
	v_permlane32_swap_b32_e32 v160, v161
	v_max3_f32 v162, v184, v160, v161
	v_max_f32_e32 v162, s97, v162
	v_sub_f32_e32 v0, v184, v162
	v_sub_f32_e32 v82, v82, v162
	v_sub_f32_e32 v83, v83, v162
	v_sub_f32_e32 v84, v84, v162
	v_sub_f32_e32 v85, v85, v162
	v_sub_f32_e32 v86, v86, v162
	v_sub_f32_e32 v87, v87, v162
	v_sub_f32_e32 v88, v88, v162
	v_sub_f32_e32 v89, v89, v162
	v_sub_f32_e32 v90, v90, v162
	v_sub_f32_e32 v91, v91, v162
	v_sub_f32_e32 v92, v92, v162
	v_sub_f32_e32 v93, v93, v162
	v_sub_f32_e32 v94, v94, v162
	v_sub_f32_e32 v95, v95, v162
	v_sub_f32_e32 v96, v96, v162
	v_sub_f32_e32 v97, v97, v162
	v_sub_f32_e32 v66, v66, v162
	v_sub_f32_e32 v67, v67, v162
	v_sub_f32_e32 v68, v68, v162
	v_sub_f32_e32 v69, v69, v162
	v_sub_f32_e32 v70, v70, v162
	v_sub_f32_e32 v71, v71, v162
	v_sub_f32_e32 v72, v72, v162
	v_sub_f32_e32 v73, v73, v162
	v_sub_f32_e32 v74, v74, v162
	v_sub_f32_e32 v75, v75, v162
	v_sub_f32_e32 v76, v76, v162
	v_sub_f32_e32 v77, v77, v162
	v_sub_f32_e32 v78, v78, v162
	v_sub_f32_e32 v79, v79, v162
	v_sub_f32_e32 v80, v80, v162
; __device__ __forceinline__ unsigned cvtpk(float lo, float hi) { unsigned r; asm("v_cvt_pk_bf16_f32 %0, %1, %2" : "=v"(r) : "v"(lo), "v"(hi)); return r; }
; template <bool MASKED>
; __device__ __forceinline__ void softmax_tile(f32x16& s0, f32x16& s1, float& m, float& l, float& alpha, unsigned mlo, unsigned mhi, bf16x8 (&pk)[4]) {
;     ...
;     alpha = __builtin_amdgcn_exp2f(m - mn); m = mn;
;     float sum = 0.f;
; #pragma unroll
;     for (int r = 0; r < 16; ++r) {
;         float p0 = __builtin_amdgcn_exp2f(s0[r] - mn), p1 = __builtin_amdgcn_exp2f(s1[r] - mn);
;         if (MASKED) { if (s0[r] <= -1e29f) p0 = 0.f; if (s1[r] <= -1e29f) p1 = 0.f; }
;         s0[r] = p0; s1[r] = p1; sum += p0 + p1;
;     }
;     l = l * alpha + sum;
; #pragma unroll
;     for (int k2 = 0; k2 < 2; ++k2) {
;         u32x4 a, b;
;         a.x = cvtpk(s0[8 * k2 + 0], s0[8 * k2 + 1]); a.y = cvtpk(s0[8 * k2 + 2], s0[8 * k2 + 3]); a.z = cvtpk(s0[8 * k2 + 4], s0[8 * k2 + 5]); a.w = cvtpk(s0[8 * k2 + 6], s0[8 * k2 + 7]);
;         b.x = cvtpk(s1[8 * k2 + 0], s1[8 * k2 + 1]); b.y = cvtpk(s1[8 * k2 + 2], s1[8 * k2 + 3]); b.z = cvtpk(s1[8 * k2 + 4], s1[8 * k2 + 5]); b.w = cvtpk(s1[8 * k2 + 6], s1[8 * k2 + 7]);
;         pk[k2] = __builtin_bit_cast(bf16x8, a); pk[2 + k2] = __builtin_bit_cast(bf16x8, b);
;     }
; }
	v_sub_f32_e32 v81, v81, v162
	v_exp_f32_e32 v0, v0
	v_exp_f32_e32 v82, v82
	v_exp_f32_e32 v83, v83
	v_exp_f32_e32 v84, v84
	v_exp_f32_e32 v85, v85
	v_exp_f32_e32 v86, v86
	v_exp_f32_e32 v87, v87
	v_exp_f32_e32 v88, v88
	v_exp_f32_e32 v89, v89
	v_exp_f32_e32 v90, v90
	v_exp_f32_e32 v91, v91
	v_exp_f32_e32 v92, v92
	v_exp_f32_e32 v93, v93
	v_exp_f32_e32 v94, v94
	v_exp_f32_e32 v95, v95
	v_exp_f32_e32 v96, v96
	v_exp_f32_e32 v97, v97
	v_exp_f32_e32 v66, v66
	v_exp_f32_e32 v67, v67
	v_exp_f32_e32 v68, v68
	v_exp_f32_e32 v69, v69
	v_exp_f32_e32 v70, v70
	v_exp_f32_e32 v71, v71
	v_exp_f32_e32 v72, v72
	v_exp_f32_e32 v73, v73
	v_exp_f32_e32 v74, v74
	v_exp_f32_e32 v75, v75
	v_exp_f32_e32 v76, v76
	v_exp_f32_e32 v77, v77
	v_exp_f32_e32 v78, v78
	v_exp_f32_e32 v79, v79
	v_exp_f32_e32 v80, v80
	v_exp_f32_e32 v81, v81
	v_pk_add_f32 v[164:165], v[82:83], v[84:85]
	v_pk_add_f32 v[166:167], v[86:87], v[88:89]
	v_pk_add_f32 v[168:169], v[90:91], v[92:93]
	v_pk_add_f32 v[170:171], v[94:95], v[96:97]
	v_pk_add_f32 v[172:173], v[66:67], v[68:69]
	v_pk_add_f32 v[174:175], v[70:71], v[72:73]
	v_pk_add_f32 v[186:187], v[74:75], v[76:77]
	v_pk_add_f32 v[188:189], v[78:79], v[80:81]
	v_pk_add_f32 v[164:165], v[164:165], v[166:167]
	v_pk_add_f32 v[168:169], v[168:169], v[170:171]
	v_pk_add_f32 v[172:173], v[172:173], v[174:175]
	v_pk_add_f32 v[186:187], v[186:187], v[188:189]
	v_pk_add_f32 v[164:165], v[164:165], v[168:169]
	v_pk_add_f32 v[172:173], v[172:173], v[186:187]
	v_pk_add_f32 v[164:165], v[164:165], v[172:173]
	v_add_f32_e32 v164, v164, v165
	v_cvt_pk_bf16_f32 v66, v66, v67
	v_cvt_pk_bf16_f32 v67, v68, v69
	v_cvt_pk_bf16_f32 v68, v70, v71
	v_cvt_pk_bf16_f32 v69, v72, v73
	v_cvt_pk_bf16_f32 v70, v74, v75
	v_cvt_pk_bf16_f32 v71, v76, v77
	v_cvt_pk_bf16_f32 v72, v78, v79
	v_cvt_pk_bf16_f32 v73, v80, v81
	v_cvt_pk_bf16_f32 v74, v82, v83
	v_cvt_pk_bf16_f32 v75, v84, v85
	v_cvt_pk_bf16_f32 v76, v86, v87
	v_cvt_pk_bf16_f32 v77, v88, v89
	v_cvt_pk_bf16_f32 v78, v90, v91
	v_cvt_pk_bf16_f32 v79, v92, v93
	v_cvt_pk_bf16_f32 v80, v94, v95
	v_cvt_pk_bf16_f32 v81, v96, v97
	v_fmac_f32_e32 v164, v183, v0
	v_mov_b32_e32 v83, v164
	v_mov_b32_e32 v82, v162
	v_cmp_neq_f32_e32 vcc, 1.0, v0
	s_cbranch_vccz .LBB0_1179
	v_pk_mul_f32 v[64:65], v[64:65], v[0:1] op_sel_hi:[1,0]
	v_pk_mul_f32 v[62:63], v[62:63], v[0:1] op_sel_hi:[1,0]
	v_pk_mul_f32 v[60:61], v[60:61], v[0:1] op_sel_hi:[1,0]
	v_pk_mul_f32 v[58:59], v[58:59], v[0:1] op_sel_hi:[1,0]
	v_pk_mul_f32 v[56:57], v[56:57], v[0:1] op_sel_hi:[1,0]
	v_pk_mul_f32 v[54:55], v[54:55], v[0:1] op_sel_hi:[1,0]
	v_pk_mul_f32 v[52:53], v[52:53], v[0:1] op_sel_hi:[1,0]
	v_pk_mul_f32 v[50:51], v[50:51], v[0:1] op_sel_hi:[1,0]
	v_pk_mul_f32 v[48:49], v[48:49], v[0:1] op_sel_hi:[1,0]
	v_pk_mul_f32 v[46:47], v[46:47], v[0:1] op_sel_hi:[1,0]
	v_pk_mul_f32 v[44:45], v[44:45], v[0:1] op_sel_hi:[1,0]
	v_pk_mul_f32 v[42:43], v[42:43], v[0:1] op_sel_hi:[1,0]
	v_pk_mul_f32 v[40:41], v[40:41], v[0:1] op_sel_hi:[1,0]
	v_pk_mul_f32 v[38:39], v[38:39], v[0:1] op_sel_hi:[1,0]
	v_pk_mul_f32 v[36:37], v[36:37], v[0:1] op_sel_hi:[1,0]
	v_pk_mul_f32 v[34:35], v[34:35], v[0:1] op_sel_hi:[1,0]
	v_pk_mul_f32 v[32:33], v[32:33], v[0:1] op_sel_hi:[1,0]
	v_pk_mul_f32 v[30:31], v[30:31], v[0:1] op_sel_hi:[1,0]
	v_pk_mul_f32 v[28:29], v[28:29], v[0:1] op_sel_hi:[1,0]
	v_pk_mul_f32 v[26:27], v[26:27], v[0:1] op_sel_hi:[1,0]
	v_pk_mul_f32 v[24:25], v[24:25], v[0:1] op_sel_hi:[1,0]
	v_pk_mul_f32 v[22:23], v[22:23], v[0:1] op_sel_hi:[1,0]
	v_pk_mul_f32 v[20:21], v[20:21], v[0:1] op_sel_hi:[1,0]
	v_pk_mul_f32 v[18:19], v[18:19], v[0:1] op_sel_hi:[1,0]
	v_pk_mul_f32 v[16:17], v[16:17], v[0:1] op_sel_hi:[1,0]
	v_pk_mul_f32 v[14:15], v[14:15], v[0:1] op_sel_hi:[1,0]
	v_pk_mul_f32 v[12:13], v[12:13], v[0:1] op_sel_hi:[1,0]
	v_pk_mul_f32 v[10:11], v[10:11], v[0:1] op_sel_hi:[1,0]
	v_pk_mul_f32 v[8:9], v[8:9], v[0:1] op_sel_hi:[1,0]
	v_pk_mul_f32 v[6:7], v[6:7], v[0:1] op_sel_hi:[1,0]
	v_pk_mul_f32 v[4:5], v[4:5], v[0:1] op_sel_hi:[1,0]
	v_pk_mul_f32 v[2:3], v[2:3], v[0:1] op_sel_hi:[1,0]
.LBB0_1179:
	v_add_u32_e32 v0, s12, v142
	v_add_u32_e32 v96, v0, v151
	v_add_u32_e32 v97, v0, v153
	v_add_u32_e32 v183, v0, v155
	v_add_u32_e32 v188, v0, v156
	v_add_u32_e32 v189, v0, v157
	v_add_u32_e32 v190, v0, v158
	v_add_u32_e32 v191, v0, v159
	v_add_u32_e32 v0, v0, v176
	v_add_u32_e32 v84, v96, v152
	v_add_u32_e32 v86, v97, v154
	v_add_u32_e32 v88, v183, v152
	v_add_u32_e32 v90, v188, v154
	v_add_u32_e32 v92, v189, v152
	v_add_u32_e32 v94, v190, v154
	v_add_u32_e32 v160, v191, v152
	v_add_u32_e32 v162, v0, v154
	v_add_u32_e32 v164, v96, v177
	v_add_u32_e32 v166, v97, v178
	v_add_u32_e32 v168, v183, v177
	v_add_u32_e32 v170, v188, v178
	v_add_u32_e32 v172, v189, v177
	v_add_u32_e32 v174, v190, v178
	v_add_u32_e32 v184, v191, v177
	v_add_u32_e32 v186, v0, v178
	ds_read_b64_tr_b16 v[84:85], v84
	ds_read_b64_tr_b16 v[86:87], v86
	ds_read_b64_tr_b16 v[88:89], v88
	ds_read_b64_tr_b16 v[90:91], v90
	ds_read_b64_tr_b16 v[92:93], v92
	ds_read_b64_tr_b16 v[94:95], v94
	ds_read_b64_tr_b16 v[160:161], v160
	ds_read_b64_tr_b16 v[162:163], v162
	ds_read_b64_tr_b16 v[164:165], v164
	ds_read_b64_tr_b16 v[166:167], v166
	ds_read_b64_tr_b16 v[168:169], v168
	ds_read_b64_tr_b16 v[170:171], v170
	ds_read_b64_tr_b16 v[172:173], v172
	ds_read_b64_tr_b16 v[174:175], v174
	ds_read_b64_tr_b16 v[184:185], v184
	ds_read_b64_tr_b16 v[186:187], v186
	s_waitcnt lgkmcnt(0)
	s_nop 0
	v_mfma_f32_32x32x16_bf16 v[50:65], v[84:87], v[74:77], v[50:65]
	v_mfma_f32_32x32x16_bf16 v[34:49], v[164:167], v[74:77], v[34:49]
	v_mfma_f32_32x32x16_bf16 v[50:65], v[88:91], v[78:81], v[50:65]
	v_mfma_f32_32x32x16_bf16 v[34:49], v[168:171], v[78:81], v[34:49]
	v_mfma_f32_32x32x16_bf16 v[50:65], v[92:95], v[66:69], v[50:65]
	v_mfma_f32_32x32x16_bf16 v[34:49], v[172:175], v[66:69], v[34:49]
	v_mfma_f32_32x32x16_bf16 v[50:65], v[160:163], v[70:73], v[50:65]
	v_mfma_f32_32x32x16_bf16 v[34:49], v[184:187], v[70:73], v[34:49]
	v_add_u32_e32 v84, v96, v179
	v_add_u32_e32 v86, v97, v180
	v_add_u32_e32 v88, v183, v179
	v_add_u32_e32 v90, v188, v180
	v_add_u32_e32 v92, v189, v179
	v_add_u32_e32 v94, v190, v180
	v_add_u32_e32 v160, v191, v179
	v_add_u32_e32 v162, v0, v180
	v_add_u32_e32 v96, v96, v181
	ds_read_b64_tr_b16 v[84:85], v84
	ds_read_b64_tr_b16 v[86:87], v86
	ds_read_b64_tr_b16 v[88:89], v88
	ds_read_b64_tr_b16 v[90:91], v90
	ds_read_b64_tr_b16 v[92:93], v92
	ds_read_b64_tr_b16 v[94:95], v94
	ds_read_b64_tr_b16 v[160:161], v160
	ds_read_b64_tr_b16 v[162:163], v162
	ds_read_b64_tr_b16 v[164:165], v96
	v_add_u32_e32 v96, v97, v182
	ds_read_b64_tr_b16 v[166:167], v96
	v_add_u32_e32 v96, v183, v181
	ds_read_b64_tr_b16 v[168:169], v96
	v_add_u32_e32 v96, v188, v182
	ds_read_b64_tr_b16 v[170:171], v96
	v_add_u32_e32 v96, v189, v181
	ds_read_b64_tr_b16 v[172:173], v96
	v_add_u32_e32 v96, v190, v182
	ds_read_b64_tr_b16 v[174:175], v96
	v_add_u32_e32 v96, v191, v181
	ds_read_b64_tr_b16 v[184:185], v96
	v_add_u32_e32 v0, v0, v182
	ds_read_b64_tr_b16 v[186:187], v0
	s_waitcnt lgkmcnt(0)
	v_mfma_f32_32x32x16_bf16 v[18:33], v[84:87], v[74:77], v[18:33]
	v_mfma_f32_32x32x16_bf16 v[2:17], v[164:167], v[74:77], v[2:17]
	v_mfma_f32_32x32x16_bf16 v[18:33], v[88:91], v[78:81], v[18:33]
	v_mfma_f32_32x32x16_bf16 v[2:17], v[168:171], v[78:81], v[2:17]
	v_mfma_f32_32x32x16_bf16 v[18:33], v[92:95], v[66:69], v[18:33]
	v_mfma_f32_32x32x16_bf16 v[2:17], v[172:175], v[66:69], v[2:17]
	v_mfma_f32_32x32x16_bf16 v[18:33], v[160:163], v[70:73], v[18:33]
	v_mfma_f32_32x32x16_bf16 v[2:17], v[184:187], v[70:73], v[2:17]
	v_mov_b32_e32 v183, v83
	s_andn2_b64 vcc, exec, s[0:1]
	s_mov_b64 s[0:1], -1
	s_cbranch_vccz .LBB0_1181
	s_branch .LBB0_1182
